# P0 row loop: sum-of-squares wave reduction by DPP + permlane swaps instead of six ds_bpermute round trips
# baseline (speedup 1.0000x reference)
; __device__ __forceinline__ unsigned pk2(float lo, float hi) { return f2bf(lo) | (f2bf(hi) << 16); }
; __device__ __forceinline__ float wave_sum(float v) {
; #pragma unroll
;     for (int o = 1; o < 64; o <<= 1) v += __shfl_xor(v, o);
;     return v;
; __global__ void __launch_bounds__(NWAVES * 64, 2) fwd_megakernel(Args args) {
;     ...
;             f32x4 v[4]; float s2 = 0.f;
; #pragma unroll
;             for (int j = 0; j < 4; ++j) { v[j] = vn[j]; s2 += (v[j].x * v[j].x + v[j].y * v[j].y) + (v[j].z * v[j].z + v[j].w * v[j].w); }
;             if (m + NGW < MROWS) { const f32x4* xr = (const f32x4*)(x + (size_t)(m + NGW) * DMODEL) + lane;
; #pragma unroll
;                 for (int j = 0; j < 4; ++j) vn[j] = __builtin_nontemporal_load(xr + 64 * j); }
;             const float rstd = 1.0f / sqrtf(wave_sum(s2) * (1.0f / DMODEL) + RMS_EPS);
;             unsigned long long* o8 = (unsigned long long*)(XN + (size_t)m * DMODEL) + lane;
;             float fa[8];
; #pragma unroll
;             for (int e = 0; e < 8; ++e) fa[e] = 0.f;
; #pragma unroll
;             for (int j = 0; j < 4; ++j) { v[j] = v[j] * rstd * gv[j];
;                 o8[64 * j] = (unsigned long long)pk2(v[j].x, v[j].y) | ((unsigned long long)pk2(v[j].z, v[j].w) << 32);
.LBB0_176:
	v_mul_f32_e32 v195, v175, v175
	v_mul_f32_e32 v196, v177, v177
	v_fmac_f32_e32 v195, v174, v174
	v_fmac_f32_e32 v196, v176, v176
	v_add_f32_e32 v195, v195, v196
	v_mul_f32_e32 v196, v171, v171
	v_mul_f32_e32 v206, v173, v173
	v_fmac_f32_e32 v196, v170, v170
	v_fmac_f32_e32 v206, v172, v172
	v_add_f32_e32 v196, v196, v206
	v_add_f32_e32 v195, v195, v196
	v_mul_f32_e32 v196, v167, v167
	v_mul_f32_e32 v206, v169, v169
	v_fmac_f32_e32 v196, v166, v166
	v_fmac_f32_e32 v206, v168, v168
	v_add_f32_e32 v196, v196, v206
	v_add_f32_e32 v195, v195, v196
	v_mul_f32_e32 v196, v163, v163
	v_mul_f32_e32 v206, v165, v165
	v_fmac_f32_e32 v196, v162, v162
	v_fmac_f32_e32 v206, v164, v164
	v_add_f32_e32 v196, v196, v206
	v_add_f32_e32 v195, v195, v196
	s_nop 1
	v_add_f32_dpp v195, v195, v195 quad_perm:[1,0,3,2] row_mask:0xf bank_mask:0xf
	s_nop 1
	v_add_f32_dpp v195, v195, v195 quad_perm:[2,3,0,1] row_mask:0xf bank_mask:0xf
	s_nop 1
	v_add_f32_dpp v195, v195, v195 row_half_mirror row_mask:0xf bank_mask:0xf
	s_nop 1
	v_add_f32_dpp v195, v195, v195 row_mirror row_mask:0xf bank_mask:0xf
	v_mov_b32_e32 v196, v195
	v_mov_b32_e32 v206, v195
	s_nop 1
	v_permlane16_swap_b32_e32 v196, v206
	v_add_f32_e32 v195, v196, v206
	v_mov_b32_e32 v196, v195
	v_mov_b32_e32 v206, v195
	s_nop 1
	v_permlane32_swap_b32_e32 v196, v206
	v_add_f32_e32 v195, v196, v206
	v_fmamk_f32 v195, v195, 0x3a800000, v202
	v_mul_f32_e32 v196, 0x4f800000, v195
	v_cmp_gt_f32_e32 vcc, s21, v195
	s_nop 1
	v_cndmask_b32_e32 v195, v195, v196, vcc
	v_sqrt_f32_e32 v196, v195
	s_nop 0
	v_add_u32_e32 v206, -1, v196
	v_add_u32_e32 v207, 1, v196
	v_fma_f32 v208, -v206, v196, v195
	v_fma_f32 v209, -v207, v196, v195
	v_cmp_ge_f32_e64 s[12:13], 0, v208
	s_nop 1
	v_cndmask_b32_e64 v196, v196, v206, s[12:13]
	v_cmp_lt_f32_e64 s[12:13], 0, v209
	s_nop 1
	v_cndmask_b32_e64 v196, v196, v207, s[12:13]
	v_mul_f32_e32 v206, 0x37800000, v196
	v_cndmask_b32_e32 v196, v196, v206, vcc
	v_cmp_class_f32_e32 vcc, v195, v203
	v_lshl_add_u64 v[206:207], s[66:67], 0, v[190:191]
	s_nop 0
	v_cndmask_b32_e32 v195, v196, v195, vcc
	v_div_scale_f32 v196, s[12:13], v195, v195, 1.0
	v_rcp_f32_e32 v208, v196
	v_div_scale_f32 v209, vcc, 1.0, v195, 1.0
	v_fma_f32 v210, -v196, v208, 1.0
	v_fmac_f32_e32 v208, v210, v208
	v_mul_f32_e32 v210, v209, v208
	v_fma_f32 v211, -v196, v210, v209
	v_fmac_f32_e32 v210, v211, v208
	v_fma_f32 v196, -v196, v210, v209
	v_div_fmas_f32 v196, v196, v208, v210
	v_div_fixup_f32 v196, v196, v195, 1.0
	v_pk_mul_f32 v[174:175], v[196:197], v[174:175] op_sel_hi:[0,1]
	v_pk_mul_f32 v[208:209], v[174:175], v[14:15]
	v_pk_mul_f32 v[176:177], v[196:197], v[176:177] op_sel_hi:[0,1]
	v_bfe_u32 v174, v208, 16, 1
	v_add3_u32 v174, v208, v174, s20
	v_bfe_u32 v175, v209, 16, 1
	v_pk_mul_f32 v[176:177], v[176:177], v[16:17]
	v_lshrrev_b32_e32 v174, 16, v174
	v_add3_u32 v175, v209, v175, s20
	v_and_or_b32 v210, v175, s22, v174
	v_bfe_u32 v174, v176, 16, 1
	v_add3_u32 v174, v176, v174, s20
	v_bfe_u32 v175, v177, 16, 1
	v_lshrrev_b32_e32 v174, 16, v174
	v_add3_u32 v175, v177, v175, s20
	v_and_or_b32 v211, v175, s22, v174
	v_add_co_u32_e32 v174, vcc, s23, v206
	v_fma_f32 v195, v208, v18, 0
	s_nop 0
	v_addc_co_u32_e32 v175, vcc, 0, v207, vcc
	global_store_dwordx2 v[174:175], v[210:211], off
	v_fma_f32 v211, v208, v22, 0
	v_fmac_f32_e32 v195, v209, v26
	v_fmac_f32_e32 v211, v209, v30
	v_fmac_f32_e32 v195, v176, v34
	v_fmac_f32_e32 v211, v176, v38
	v_pk_mul_f32 v[170:171], v[196:197], v[170:171] op_sel_hi:[0,1]
	v_fmac_f32_e32 v195, v177, v42
	v_fmac_f32_e32 v211, v177, v46
	v_pk_mul_f32 v[170:171], v[170:171], v[10:11]
	v_pk_mul_f32 v[172:173], v[196:197], v[172:173] op_sel_hi:[0,1]
	v_fmac_f32_e32 v195, v170, v50
	v_fmac_f32_e32 v211, v170, v54
	v_pk_mul_f32 v[172:173], v[172:173], v[12:13]
	v_fmac_f32_e32 v195, v171, v58
	v_fmac_f32_e32 v211, v171, v62
	v_fma_f32 v206, v208, v19, 0
	v_fma_f32 v212, v208, v23, 0
	v_fmac_f32_e32 v195, v172, v66
	v_fmac_f32_e32 v211, v172, v70
	v_pk_mul_f32 v[166:167], v[196:197], v[166:167] op_sel_hi:[0,1]
	v_fma_f32 v207, v208, v20, 0
	v_fma_f32 v213, v208, v24, 0
	v_fmac_f32_e32 v206, v209, v27
	v_fmac_f32_e32 v212, v209, v31
	v_fmac_f32_e32 v195, v173, v74
	v_fmac_f32_e32 v211, v173, v78
	v_pk_mul_f32 v[166:167], v[166:167], v[6:7]
	v_fma_f32 v210, v208, v21, 0
	v_fma_f32 v208, v208, v25, 0
	v_fmac_f32_e32 v207, v209, v28
	v_fmac_f32_e32 v213, v209, v32
	v_fmac_f32_e32 v206, v176, v35
	v_fmac_f32_e32 v212, v176, v39
	v_pk_mul_f32 v[168:169], v[196:197], v[168:169] op_sel_hi:[0,1]
	v_fmac_f32_e32 v195, v166, v82
	v_fmac_f32_e32 v211, v166, v86
	v_fmac_f32_e32 v210, v209, v29
	v_fmac_f32_e32 v208, v209, v33
	v_fmac_f32_e32 v207, v176, v36
	v_fmac_f32_e32 v213, v176, v40
	v_fmac_f32_e32 v206, v177, v43
	v_fmac_f32_e32 v212, v177, v47
	v_pk_mul_f32 v[168:169], v[168:169], v[8:9]
	v_fmac_f32_e32 v195, v167, v90
	v_fmac_f32_e32 v211, v167, v94
	v_fmac_f32_e32 v210, v176, v37
	v_fmac_f32_e32 v208, v176, v41
	v_fmac_f32_e32 v207, v177, v44
	v_fmac_f32_e32 v213, v177, v48
	v_fmac_f32_e32 v206, v170, v51
	v_fmac_f32_e32 v212, v170, v55
	v_fmac_f32_e32 v195, v168, v98
	v_fmac_f32_e32 v211, v168, v102
	v_pk_mul_f32 v[162:163], v[196:197], v[162:163] op_sel_hi:[0,1]
	v_fmac_f32_e32 v210, v177, v45
	v_fmac_f32_e32 v208, v177, v49
	v_fmac_f32_e32 v207, v170, v52
	v_fmac_f32_e32 v213, v170, v56
	v_fmac_f32_e32 v206, v171, v59
	v_fmac_f32_e32 v212, v171, v63
	v_fmac_f32_e32 v195, v169, v106
	v_fmac_f32_e32 v211, v169, v110
	v_pk_mul_f32 v[162:163], v[162:163], v[2:3]
	v_fmac_f32_e32 v210, v170, v53
	v_fmac_f32_e32 v208, v170, v57
	v_fmac_f32_e32 v207, v171, v60
	v_fmac_f32_e32 v213, v171, v64
; #define LAS __attribute__((address_space(3)))
; __device__ __forceinline__ unsigned pk2(float lo, float hi) { return f2bf(lo) | (f2bf(hi) << 16); }
; __global__ void __launch_bounds__(NWAVES * 64, 2) fwd_megakernel(Args args) {
;     ...
;             for (int j = 0; j < 4; ++j) { v[j] = v[j] * rstd * gv[j];
;                 o8[64 * j] = (unsigned long long)pk2(v[j].x, v[j].y) | ((unsigned long long)pk2(v[j].z, v[j].w) << 32);
; #pragma unroll
;                 for (int i = 0; i < 4; ++i) { const int k = 256 * j + 4 * lane + i; const f32x4 wa = *(const LAS f32x4*)(Wf + k * 8), wb = *(const LAS f32x4*)(Wf + k * 8 + 4); const float hk = v[j][i];
;                     fa[0] += hk * wa[0]; fa[1] += hk * wa[1]; fa[2] += hk * wa[2]; fa[3] += hk * wa[3]; fa[4] += hk * wb[0]; fa[5] += hk * wb[1]; fa[6] += hk * wb[2]; fa[7] += hk * wb[3]; } }
;             float r4[4], r2[2], r1;
;             { const bool h = (lane & 32) != 0;
; #pragma unroll
;               for (int e = 0; e < 4; ++e) { const float snd = h ? fa[e] : fa[e + 4], kp = h ? fa[e + 4] : fa[e]; r4[e] = kp + __shfl_xor(snd, 32); } }
;             { const bool h = (lane & 16) != 0;
; #pragma unroll
;               for (int e = 0; e < 2; ++e) { const float snd = h ? r4[e] : r4[e + 2], kp = h ? r4[e + 2] : r4[e]; r2[e] = kp + __shfl_xor(snd, 16); } }
;             { const bool h = (lane & 8) != 0; const float snd = h ? r2[0] : r2[1], kp = h ? r2[1] : r2[0]; r1 = kp + __shfl_xor(snd, 8); }
;             r1 += __shfl_xor(r1, 4); r1 += __shfl_xor(r1, 2); r1 += __shfl_xor(r1, 1);
	v_fmac_f32_e32 v206, v172, v67
	v_fmac_f32_e32 v212, v172, v71
	v_pk_mul_f32 v[164:165], v[196:197], v[164:165] op_sel_hi:[0,1]
	v_fmac_f32_e32 v195, v162, v114
	v_fmac_f32_e32 v211, v162, v118
	v_fmac_f32_e32 v210, v171, v61
	v_fmac_f32_e32 v208, v171, v65
	v_fmac_f32_e32 v207, v172, v68
	v_fmac_f32_e32 v213, v172, v72
	v_fmac_f32_e32 v206, v173, v75
	v_fmac_f32_e32 v212, v173, v79
	v_pk_mul_f32 v[164:165], v[164:165], v[4:5]
	v_fmac_f32_e32 v195, v163, v122
	v_fmac_f32_e32 v211, v163, v126
	v_bfe_u32 v176, v170, 16, 1
	v_fmac_f32_e32 v210, v172, v69
	v_fmac_f32_e32 v208, v172, v73
	v_fmac_f32_e32 v207, v173, v76
	v_fmac_f32_e32 v213, v173, v80
	v_fmac_f32_e32 v206, v166, v83
	v_fmac_f32_e32 v212, v166, v87
	v_fmac_f32_e32 v195, v164, v130
	v_fmac_f32_e32 v211, v164, v134
	v_add3_u32 v176, v170, v176, s20
	v_fmac_f32_e32 v210, v173, v77
	v_fmac_f32_e32 v208, v173, v81
	v_bfe_u32 v170, v166, 16, 1
	v_fmac_f32_e32 v207, v166, v84
	v_fmac_f32_e32 v213, v166, v88
	v_fmac_f32_e32 v206, v167, v91
	v_fmac_f32_e32 v212, v167, v95
	v_fmac_f32_e32 v195, v165, v138
	v_fmac_f32_e32 v211, v165, v142
	v_add3_u32 v170, v166, v170, s20
	v_fmac_f32_e32 v210, v166, v85
	v_fmac_f32_e32 v208, v166, v89
	v_fmac_f32_e32 v207, v167, v92
	v_fmac_f32_e32 v213, v167, v96
	v_fmac_f32_e32 v206, v168, v99
	v_fmac_f32_e32 v212, v168, v103
	v_cndmask_b32_e64 v166, v195, v211, s[0:1]
	v_fmac_f32_e32 v210, v167, v93
	v_fmac_f32_e32 v208, v167, v97
	v_fmac_f32_e32 v207, v168, v100
	v_fmac_f32_e32 v213, v168, v104
	v_fmac_f32_e32 v206, v169, v107
	v_fmac_f32_e32 v212, v169, v111
	ds_bpermute_b32 v166, v201, v166
	v_bfe_u32 v177, v171, 16, 1
	v_fmac_f32_e32 v210, v168, v101
	v_fmac_f32_e32 v208, v168, v105
	v_fmac_f32_e32 v207, v169, v108
	v_fmac_f32_e32 v213, v169, v112
	v_fmac_f32_e32 v206, v162, v115
	v_fmac_f32_e32 v212, v162, v119
	v_lshrrev_b32_e32 v176, 16, v176
	v_add3_u32 v177, v171, v177, s20
	v_fmac_f32_e32 v210, v169, v109
	v_fmac_f32_e32 v208, v169, v113
	v_fmac_f32_e32 v207, v162, v116
	v_fmac_f32_e32 v213, v162, v120
	v_fmac_f32_e32 v206, v163, v123
	v_fmac_f32_e32 v212, v163, v127
	v_and_or_b32 v176, v177, s22, v176
	v_bfe_u32 v177, v172, 16, 1
	v_bfe_u32 v171, v167, 16, 1
	v_fmac_f32_e32 v210, v162, v117
	v_fmac_f32_e32 v208, v162, v121
	v_fmac_f32_e32 v207, v163, v124
	v_fmac_f32_e32 v213, v163, v128
	v_fmac_f32_e32 v206, v164, v131
	v_fmac_f32_e32 v212, v164, v135
	v_add3_u32 v177, v172, v177, s20
	v_bfe_u32 v209, v173, 16, 1
	v_add3_u32 v171, v167, v171, s20
	v_fmac_f32_e32 v210, v163, v125
	v_fmac_f32_e32 v208, v163, v129
	v_fmac_f32_e32 v207, v164, v132
	v_fmac_f32_e32 v213, v164, v136
	v_fmac_f32_e32 v206, v165, v139
	v_fmac_f32_e32 v212, v165, v143
	v_cndmask_b32_e64 v167, v211, v195, s[0:1]
	v_lshrrev_b32_e32 v177, 16, v177
	v_add3_u32 v209, v173, v209, s20
	v_fmac_f32_e32 v210, v164, v133
	v_fmac_f32_e32 v208, v164, v137
	v_fmac_f32_e32 v207, v165, v140
	v_fmac_f32_e32 v213, v165, v144
	s_waitcnt lgkmcnt(0)
	v_add_f32_e32 v166, v167, v166
	v_cndmask_b32_e64 v167, v206, v212, s[0:1]
	v_and_or_b32 v177, v209, s22, v177
	v_fmac_f32_e32 v210, v165, v141
	v_fmac_f32_e32 v208, v165, v145
	ds_bpermute_b32 v167, v201, v167
	v_cndmask_b32_e64 v173, v207, v213, s[0:1]
	global_store_dwordx2 v[174:175], v[176:177], off offset:512
	ds_bpermute_b32 v173, v201, v173
	v_cndmask_b32_e64 v176, v210, v208, s[0:1]
	v_lshrrev_b32_e32 v170, 16, v170
	ds_bpermute_b32 v176, v201, v176
	v_and_or_b32 v170, v171, s22, v170
	v_bfe_u32 v171, v168, 16, 1
	v_add3_u32 v171, v168, v171, s20
	v_cndmask_b32_e64 v168, v212, v206, s[0:1]
	s_waitcnt lgkmcnt(2)
	v_add_f32_e32 v167, v168, v167
	v_cndmask_b32_e64 v168, v213, v207, s[0:1]
	s_waitcnt lgkmcnt(1)
	v_add_f32_e32 v168, v168, v173
	v_cndmask_b32_e64 v173, v208, v210, s[0:1]
	s_waitcnt lgkmcnt(0)
	v_add_f32_e32 v173, v173, v176
	v_cndmask_b32_e64 v176, v166, v168, s[4:5]
	v_cndmask_b32_e64 v177, v167, v173, s[4:5]
	ds_bpermute_b32 v176, v200, v176
	ds_bpermute_b32 v177, v200, v177
	v_cndmask_b32_e64 v166, v168, v166, s[4:5]
	v_cndmask_b32_e64 v167, v173, v167, s[4:5]
	v_bfe_u32 v172, v169, 16, 1
	s_waitcnt lgkmcnt(1)
	v_add_f32_e32 v166, v166, v176
	s_waitcnt lgkmcnt(0)
	v_add_f32_e32 v167, v167, v177
	v_cndmask_b32_e64 v168, v166, v167, s[6:7]
	ds_bpermute_b32 v168, v199, v168
	v_cndmask_b32_e64 v166, v167, v166, s[6:7]
	v_lshrrev_b32_e32 v171, 16, v171
	v_add3_u32 v169, v169, v172, s20
	v_and_or_b32 v171, v169, s22, v171
	s_waitcnt lgkmcnt(0)
	v_add_f32_e32 v166, v166, v168
	ds_bpermute_b32 v167, v198, v166
	v_bfe_u32 v168, v163, 16, 1
	v_bfe_u32 v169, v162, 16, 1
	v_add3_u32 v163, v163, v168, s20
	v_add3_u32 v162, v162, v169, s20
	s_waitcnt lgkmcnt(0)
	v_add_f32_e32 v167, v166, v167
	ds_bpermute_b32 v168, v197, v167
	v_lshrrev_b32_e32 v162, 16, v162
	v_and_or_b32 v166, v163, s22, v162
	v_bfe_u32 v162, v164, 16, 1
	v_add3_u32 v162, v164, v162, s20
	v_lshrrev_b32_e32 v164, 16, v162
	s_waitcnt lgkmcnt(0)
	v_add_f32_e32 v162, v167, v168
	ds_bpermute_b32 v163, v179, v162
	v_bfe_u32 v167, v165, 16, 1
	v_add3_u32 v165, v165, v167, s20
	v_and_or_b32 v167, v165, s22, v164
	global_store_dwordx2 v[174:175], v[170:171], off offset:1024
	global_store_dwordx2 v[174:175], v[166:167], off offset:1536
	s_and_saveexec_b64 s[12:13], s[8:9]
	s_cbranch_execz .LBB0_173
; __device__ __forceinline__ float log_sigmoid(float y) { return fminf(y, 0.f) - log1pf(expf(-fabsf(y))); }
; __global__ void __launch_bounds__(NWAVES * 64, 2) fwd_megakernel(Args args) {
;     ...
;             { const bool h = (lane & 8) != 0; const float snd = h ? r2[0] : r2[1], kp = h ? r2[1] : r2[0]; r1 = kp + __shfl_xor(snd, 8); }
;             r1 += __shfl_xor(r1, 4); r1 += __shfl_xor(r1, 2); r1 += __shfl_xor(r1, 1);
;             if ((lane & 7) == 0) { const int e = lane >> 3; LF[(size_t)m * 8 + e] = log_sigmoid(r1 + fbias[e]); }
	s_waitcnt lgkmcnt(0)
	v_add_f32_e32 v162, v162, v163
	v_add_f32_e32 v162, v162, v214
	v_mul_f32_e64 v163, |v162|, s26
	v_fma_f32 v164, |v162|, s26, -v163
	v_rndne_f32_e32 v165, v163
	v_fma_f32 v164, |v162|, s27, v164
	v_sub_f32_e32 v163, v163, v165
	v_add_f32_e32 v163, v163, v164
	v_cvt_i32_f32_e32 v165, v165
	v_exp_f32_e32 v163, v163
	v_cmp_ngt_f32_e64 vcc, |v162|, s28
	v_min_f32_e32 v176, 0, v162
	v_ldexp_f32 v163, v163, v165
	v_cndmask_b32_e32 v163, 0, v163, vcc
	v_cmp_nlt_f32_e64 vcc, |v162|, s29
	s_nop 1
	v_cndmask_b32_e32 v177, v205, v163, vcc
	v_add_f32_e32 v164, 1.0, v177
	v_add_f32_e32 v165, -1.0, v164
	v_frexp_mant_f32_e32 v166, v164
	v_cvt_f64_f32_e32 v[162:163], v164
	v_sub_f32_e32 v167, v165, v164
	v_frexp_exp_i32_f64_e32 v162, v[162:163]
	v_cmp_gt_f32_e32 vcc, s31, v166
	v_sub_f32_e32 v165, v177, v165
	v_add_f32_e32 v163, 1.0, v167
	v_subbrev_co_u32_e32 v162, vcc, 0, v162, vcc
	v_add_f32_e32 v163, v165, v163
	v_sub_u32_e32 v165, 0, v162
	v_ldexp_f32 v164, v164, v165
	v_add_f32_e32 v166, -1.0, v164
	v_add_f32_e32 v167, 1.0, v164
	v_ldexp_f32 v163, v163, v165
	v_add_f32_e32 v165, 1.0, v166
	v_add_f32_e32 v168, -1.0, v167
	v_sub_f32_e32 v165, v164, v165
	v_sub_f32_e32 v164, v164, v168
	v_add_f32_e32 v168, v163, v165
	v_add_f32_e32 v163, v163, v164
	v_add_f32_e32 v170, v167, v163
	v_rcp_f32_e32 v171, v170
	v_add_f32_e32 v165, v166, v168
	v_sub_f32_e32 v166, v166, v165
	v_sub_f32_e32 v164, v167, v170
	v_mul_f32_e32 v173, v165, v171
	v_add_f32_e32 v172, v168, v166
	v_mul_f32_e32 v166, v170, v173
	v_add_f32_e32 v163, v163, v164
	v_fma_f32 v168, v173, v170, -v166
	v_fmac_f32_e32 v168, v173, v163
	v_add_f32_e32 v164, v166, v168
	v_sub_f32_e32 v167, v165, v164
	v_mov_b32_e32 v169, v164
	v_pk_add_f32 v[164:165], v[164:165], v[166:167] neg_lo:[0,1] neg_hi:[0,1]
	v_cvt_f32_i32_e32 v162, v162
	v_pk_add_f32 v[164:165], v[164:165], v[168:169] neg_lo:[0,1] neg_hi:[0,1]
	v_cmp_neq_f32_e32 vcc, s30, v177
	v_add_f32_e32 v165, v172, v165
	v_add_f32_e32 v164, v164, v165
	v_add_f32_e32 v165, v167, v164
	v_mul_f32_e32 v169, v171, v165
	v_mul_f32_e32 v166, v170, v169
	v_sub_f32_e32 v167, v167, v165
	v_add_f32_e32 v174, v173, v169
	v_fma_f32 v168, v169, v170, -v166
	v_add_f32_e32 v172, v164, v167
	v_sub_f32_e32 v164, v174, v173
	v_fmac_f32_e32 v168, v169, v163
	v_sub_f32_e32 v163, v169, v164
	v_add_f32_e32 v164, v166, v168
	v_sub_f32_e32 v167, v165, v164
	v_mov_b32_e32 v169, v164
	v_pk_add_f32 v[164:165], v[164:165], v[166:167] neg_lo:[0,1] neg_hi:[0,1]
	s_nop 0
	v_pk_add_f32 v[164:165], v[164:165], v[168:169] neg_lo:[0,1] neg_hi:[0,1]
	s_nop 0
	v_add_f32_e32 v165, v172, v165
	v_add_f32_e32 v164, v164, v165
	v_add_f32_e32 v164, v167, v164
	v_mul_f32_e32 v164, v171, v164
	v_add_f32_e32 v163, v163, v164
	v_add_f32_e32 v164, v174, v163
	v_mul_f32_e32 v166, v164, v164
	v_sub_f32_e32 v167, v164, v174
	v_fmamk_f32 v168, v166, 0x3e9b6dac, v204
	v_sub_f32_e32 v167, v163, v167
	v_mul_f32_e32 v163, v164, v166
	v_fmaak_f32 v195, v166, v168, 0x3f2aaada
	v_ldexp_f32 v169, v167, 1
	v_pk_mul_f32 v[166:167], v[162:163], v[194:195]
	v_ldexp_f32 v165, v164, 1
	v_fma_f32 v164, v162, s33, -v166
	v_fmac_f32_e32 v164, 0xb102e308, v162
	v_pk_add_f32 v[162:163], v[166:167], v[164:165]
	v_mov_b32_e32 v168, v166
	v_sub_f32_e32 v172, v163, v165
	v_pk_add_f32 v[170:171], v[162:163], v[166:167] neg_lo:[0,1] neg_hi:[0,1]
	v_sub_f32_e32 v166, v167, v172
	v_add_f32_e32 v169, v169, v166
	v_pk_add_f32 v[166:167], v[162:163], v[168:169]
	v_mov_b32_e32 v165, v162
	v_mov_b32_e32 v171, v167
	v_pk_add_f32 v[174:175], v[164:165], v[170:171] neg_lo:[0,1] neg_hi:[0,1]
	v_pk_add_f32 v[164:165], v[164:165], v[170:171]
	v_mov_b32_e32 v173, v162
	v_pk_add_f32 v[170:171], v[164:165], v[162:163] op_sel:[1,0] op_sel_hi:[0,1] neg_lo:[0,1] neg_hi:[0,1]
	v_mov_b32_e32 v172, v169
	v_mov_b32_e32 v168, v167
	v_mov_b32_e32 v169, v165
	v_pk_mov_b32 v[162:163], v[162:163], v[170:171] op_sel:[1,0]
	v_pk_add_f32 v[166:167], v[166:167], v[170:171] op_sel_hi:[1,0] neg_lo:[0,1] neg_hi:[0,1]
	v_pk_add_f32 v[162:163], v[168:169], v[162:163] neg_lo:[0,1] neg_hi:[0,1]
	v_mov_b32_e32 v166, v174
	v_pk_add_f32 v[162:163], v[172:173], v[162:163] neg_lo:[0,1] neg_hi:[0,1]
	v_mov_b32_e32 v175, v165
	v_pk_add_f32 v[166:167], v[166:167], v[162:163]
	s_nop 0
	v_pk_add_f32 v[168:169], v[166:167], v[166:167] op_sel:[0,1] op_sel_hi:[1,0]
	s_nop 0
	v_pk_add_f32 v[164:165], v[164:165], v[168:169] op_sel:[1,0] op_sel_hi:[0,1]
	v_mov_b32_e32 v167, v164
	v_mov_b32_e32 v163, v168
	v_pk_add_f32 v[168:169], v[166:167], v[174:175] neg_lo:[0,1] neg_hi:[0,1]
	s_nop 0
	v_sub_f32_e32 v165, v166, v168
	v_pk_add_f32 v[162:163], v[162:163], v[168:169] neg_lo:[0,1] neg_hi:[0,1]
	v_sub_f32_e32 v165, v174, v165
	v_add_f32_e32 v162, v162, v165
	v_add_f32_e32 v162, v162, v163
	v_add_f32_e32 v162, v164, v162
	v_cndmask_b32_e32 v162, v205, v162, vcc
	v_cmp_lt_f32_e64 vcc, |v177|, s34
	s_nop 1
	v_cndmask_b32_e32 v162, v162, v177, vcc
	v_sub_f32_e32 v164, v176, v162
	v_lshl_add_u64 v[162:163], s[66:67], 0, v[188:189]
	global_store_dword v[162:163], v164, off
	s_branch .LBB0_173
